# same as previous best plus one extra lgkmcnt wait per GDN sub-chunk that keeps nominal outstanding LDS ops <= 15 (robustness)
# speedup vs baseline: 1.0005x; 1.0005x over previous
.LBB0_967:
	v_or_b32_e32 v1, s65, v137
	v_lshlrev_b32_e32 v0, 1, v143
	v_mul_lo_u32 v1, v1, s10
	v_add3_u32 v3, 0, v1, v0
	v_mul_u32_u24_e32 v1, 40, v137
	s_add_i32 s0, 0, 0x1f400
	v_lshlrev_b32_e32 v1, 1, v1
	s_waitcnt lgkmcnt(0)
	s_barrier
	s_waitcnt vmcnt(0) lgkmcnt(0)
	v_add3_u32 v88, s0, v0, v1
	ds_read_b128 v[68:71], v88
	ds_read_b128 v[72:75], v3 offset:55296
	s_waitcnt lgkmcnt(0)
	v_mfma_f32_16x16x32_bf16 v[68:71], v[68:71], v[72:75], 0
	ds_read_b128 v[72:75], v3 offset:34816
	v_add3_u32 v89, s47, v0, v1
	ds_read_b128 v[76:79], v89
	s_waitcnt lgkmcnt(0)
	v_mfma_f32_16x16x32_bf16 v[72:75], v[72:75], v[76:79], 0
	v_add_u32_e32 v108, 0, v139
	v_add_u32_e32 v107, s76, v140
	v_add_u32_e32 v101, s85, v139
	s_nop 4
	v_xor_b32_e32 v0, 0x80000000, v73
	v_xor_b32_e32 v1, 0x80000000, v72
	v_cvt_pk_bf16_f32 v0, v1, v0
	v_xor_b32_e32 v1, 0x80000000, v74
	v_xor_b32_e32 v72, 0x80000000, v75
	v_cvt_pk_bf16_f32 v1, v1, v72
	v_mul_u32_u24_e32 v72, 0x110, v137
	v_add3_u32 v92, s67, v139, v72
	ds_write_b64 v92, v[0:1]
	ds_read_b128 v[72:75], v88 offset:1280
	ds_read_b128 v[76:79], v3 offset:55328
	s_waitcnt lgkmcnt(0)
	v_mfma_f32_16x16x32_bf16 v[80:83], v[72:75], v[76:79], 0
	ds_read_b128 v[72:75], v3 offset:34848
	ds_read_b128 v[76:79], v89 offset:1280
	v_mad_u32_u24 v103, v137, s10, v108
	v_or_b32_e32 v110, 16, v137
	s_waitcnt lgkmcnt(0)
	v_mfma_f32_16x16x32_bf16 v[72:75], v[72:75], v[76:79], 0
	v_mad_u32_u24 v104, v110, s10, v108
	v_or_b32_e32 v109, 32, v137
	v_or_b32_e32 v100, 48, v137
	s_nop 4
	v_xor_b32_e32 v0, 0x80000000, v73
	v_xor_b32_e32 v1, 0x80000000, v72
	v_cvt_pk_bf16_f32 v0, v1, v0
	v_xor_b32_e32 v1, 0x80000000, v74
	v_xor_b32_e32 v72, 0x80000000, v75
	v_cvt_pk_bf16_f32 v1, v1, v72
	ds_write_b64 v92, v[0:1] offset:4352
	ds_read_b128 v[72:75], v88 offset:2560
	ds_read_b128 v[76:79], v3 offset:55360
	s_waitcnt lgkmcnt(0)
	v_mfma_f32_16x16x32_bf16 v[76:79], v[72:75], v[76:79], 0
	ds_read_b128 v[72:75], v3 offset:34880
	ds_read_b128 v[84:87], v89 offset:2560
	s_add_i32 s56, s56, 1
	s_add_i32 s3, s3, 64
	s_waitcnt lgkmcnt(0)
	v_mfma_f32_16x16x32_bf16 v[72:75], v[72:75], v[84:87], 0
	s_add_i32 s96, s96, 1
	s_cmpk_eq_i32 s3, 0x900
	s_nop 5
	v_xor_b32_e32 v0, 0x80000000, v73
	v_xor_b32_e32 v1, 0x80000000, v72
	v_cvt_pk_bf16_f32 v0, v1, v0
	v_xor_b32_e32 v1, 0x80000000, v74
	v_xor_b32_e32 v72, 0x80000000, v75
	v_cvt_pk_bf16_f32 v1, v1, v72
	ds_write_b64 v92, v[0:1] offset:8704
	ds_read_b128 v[72:75], v88 offset:3840
	ds_read_b128 v[84:87], v3 offset:55392
	s_waitcnt lgkmcnt(0)
	v_mfma_f32_16x16x32_bf16 v[72:75], v[72:75], v[84:87], 0
	ds_read_b128 v[84:87], v3 offset:34912
	ds_read_b128 v[88:91], v89 offset:3840
	s_waitcnt lgkmcnt(0)
	v_mfma_f32_16x16x32_bf16 v[84:87], v[84:87], v[88:91], 0
	v_cvt_pk_bf16_f32 v88, v40, v41
	v_cvt_pk_bf16_f32 v89, v42, v43
	s_nop 5
	v_xor_b32_e32 v0, 0x80000000, v85
	v_xor_b32_e32 v1, 0x80000000, v84
	v_cvt_pk_bf16_f32 v0, v1, v0
	v_xor_b32_e32 v1, 0x80000000, v86
	v_xor_b32_e32 v3, 0x80000000, v87
	v_cvt_pk_bf16_f32 v1, v1, v3
	ds_write_b64 v92, v[0:1] offset:13056
	v_add_u32_e32 v0, 0, v140
	s_waitcnt lgkmcnt(0)
	v_add_u32_e32 v106, 0x24a80, v0
	v_add_u32_e32 v102, 0x24b80, v0
	v_mul_u32_u24_e32 v0, 0x88, v137
	v_lshl_add_u32 v0, v0, 1, v108
	s_waitcnt lgkmcnt(0)
	s_barrier
	v_mov_b32_e32 v218, 0
	v_mov_b32_e32 v219, 0
	v_mov_b32_e32 v234, 0
	v_mov_b32_e32 v235, 0
	v_mov_b32_e32 v242, 0
	v_mov_b32_e32 v243, 0
	v_mov_b32_e32 v246, 0
	v_mov_b32_e32 v247, 0
	v_mov_b32_e32 v250, s76
	ds_read_b128 v[236:239], v250 offset:768
	ds_read_b64 v[154:155], v0
	ds_read_b64 v[156:157], v0 offset:32
	ds_read_b64 v[170:171], v0 offset:17408
	ds_read_b64 v[172:173], v0 offset:17440
	ds_read_b64 v[158:159], v0 offset:64
	ds_read_b64 v[160:161], v0 offset:96
	ds_read_b64 v[174:175], v0 offset:17472
	ds_read_b64 v[176:177], v0 offset:17504
	v_mad_u32_u24 v252, v137, s84, v101
	v_lshlrev_b32_e32 v92, 1, v137
	v_mul_u32_u24_e32 v93, 0x440, v138
	v_add3_u32 v253, s89, v92, v93
	v_cvt_pk_bf16_f32 v186, v36, v37
	v_cvt_pk_bf16_f32 v187, v38, v39
	v_cvt_pk_bf16_f32 v188, v40, v41
	v_cvt_pk_bf16_f32 v189, v42, v43
	ds_read_b64 v[162:163], v0 offset:128
	ds_read_b64 v[164:165], v0 offset:160
	ds_read_b64 v[178:179], v0 offset:17536
	ds_read_b64 v[180:181], v0 offset:17568
	s_waitcnt lgkmcnt(8)
	v_mfma_f32_16x16x32_bf16 v[68:71], v[154:157], v[186:189], v[68:71]
	v_mfma_f32_16x16x32_bf16 v[84:87], v[170:173], v[186:189], 0
	v_cvt_pk_bf16_f32 v190, v44, v45
	v_cvt_pk_bf16_f32 v191, v46, v47
	v_cvt_pk_bf16_f32 v192, v48, v49
	v_cvt_pk_bf16_f32 v193, v50, v51
	ds_read_b64 v[166:167], v0 offset:192
	ds_read_b64 v[168:169], v0 offset:224
	ds_read_b64 v[182:183], v0 offset:17600
	ds_read_b64 v[184:185], v0 offset:17632
	s_waitcnt lgkmcnt(8)
	v_mfma_f32_16x16x32_bf16 v[68:71], v[158:161], v[190:193], v[68:71]
	v_mfma_f32_16x16x32_bf16 v[84:87], v[174:177], v[190:193], v[84:87]
	v_cvt_pk_bf16_f32 v194, v52, v53
	v_cvt_pk_bf16_f32 v195, v54, v55
	v_cvt_pk_bf16_f32 v196, v56, v57
	v_cvt_pk_bf16_f32 v197, v58, v59
	ds_read_b64 v[202:203], v103 offset:34816
	ds_read_b64 v[204:205], v104 offset:34816
	ds_read_b64 v[206:207], v104 offset:37376
	ds_read_b64 v[208:209], v104 offset:39936
	s_waitcnt lgkmcnt(8)
	v_mfma_f32_16x16x32_bf16 v[68:71], v[162:165], v[194:197], v[68:71]
	v_mfma_f32_16x16x32_bf16 v[84:87], v[178:181], v[194:197], v[84:87]
	v_cvt_pk_bf16_f32 v198, v60, v61
	v_cvt_pk_bf16_f32 v199, v62, v63
	v_cvt_pk_bf16_f32 v200, v64, v65
	v_cvt_pk_bf16_f32 v201, v66, v67
	ds_read_b64 v[210:211], v103 offset:45056
	ds_read_b64 v[212:213], v103 offset:47616
	ds_read_b64 v[214:215], v103 offset:50176
	ds_read_b64 v[216:217], v103 offset:52736
	s_waitcnt lgkmcnt(8)
	v_mfma_f32_16x16x32_bf16 v[68:71], v[166:169], v[198:201], v[68:71]
	v_mfma_f32_16x16x32_bf16 v[84:87], v[182:185], v[198:201], v[84:87]
	ds_read_b128 v[220:223], v106
	ds_read_b128 v[224:227], v107 offset:512
	ds_read_b128 v[228:231], v102
	ds_read_b64 v[232:233], v252
	v_pk_mul_f32 v[36:37], v[36:37], v[236:237] op_sel_hi:[1,0]
	v_pk_mul_f32 v[38:39], v[38:39], v[236:237] op_sel_hi:[1,0]
	v_pk_mul_f32 v[40:41], v[40:41], v[236:237] op_sel_hi:[1,0]
	v_pk_mul_f32 v[42:43], v[42:43], v[236:237] op_sel_hi:[1,0]
	v_pk_mul_f32 v[44:45], v[44:45], v[236:237] op_sel_hi:[1,0]
	v_pk_mul_f32 v[46:47], v[46:47], v[236:237] op_sel_hi:[1,0]
	v_pk_mul_f32 v[48:49], v[48:49], v[236:237] op_sel_hi:[1,0]
	v_pk_mul_f32 v[50:51], v[50:51], v[236:237] op_sel_hi:[1,0]
	v_pk_mul_f32 v[52:53], v[52:53], v[236:237] op_sel_hi:[1,0]
	v_pk_mul_f32 v[54:55], v[54:55], v[236:237] op_sel_hi:[1,0]
	v_pk_mul_f32 v[56:57], v[56:57], v[236:237] op_sel_hi:[1,0]
	v_pk_mul_f32 v[58:59], v[58:59], v[236:237] op_sel_hi:[1,0]
	v_pk_mul_f32 v[60:61], v[60:61], v[236:237] op_sel_hi:[1,0]
	v_pk_mul_f32 v[62:63], v[62:63], v[236:237] op_sel_hi:[1,0]
	v_pk_mul_f32 v[64:65], v[64:65], v[236:237] op_sel_hi:[1,0]
	v_pk_mul_f32 v[66:67], v[66:67], v[236:237] op_sel_hi:[1,0]
	s_waitcnt lgkmcnt(2)
	v_cvt_pk_bf16_f32 v240, v68, v69
	v_cvt_pk_bf16_f32 v241, v70, v71
	v_pk_mul_f32 v[88:89], v[68:69], v[220:221]
	v_pk_mul_f32 v[90:91], v[70:71], v[222:223]
	v_cvt_pk_bf16_f32 v244, v88, v89
	v_cvt_pk_bf16_f32 v245, v90, v91
	v_pk_mul_f32 v[84:85], v[84:85], v[224:225]
	v_pk_mul_f32 v[86:87], v[86:87], v[226:227]
	s_waitcnt lgkmcnt(0)
	v_mfma_f32_16x16x32_bf16 v[36:39], v[202:205], v[244:247], v[36:39]
	v_mfma_f32_16x16x32_bf16 v[40:43], v[204:207], v[244:247], v[40:43]
	v_mfma_f32_16x16x32_bf16 v[84:87], v[232:235], v[240:243], v[84:87]
	v_add_u32_e32 v250, 4352, v0
	v_mfma_f32_16x16x32_bf16 v[44:47], v[206:209], v[244:247], v[44:47]
	v_mfma_f32_16x16x32_bf16 v[48:51], v[208:211], v[244:247], v[48:51]
	v_mfma_f32_16x16x32_bf16 v[52:55], v[210:213], v[244:247], v[52:55]
	v_mfma_f32_16x16x32_bf16 v[56:59], v[212:215], v[244:247], v[56:59]
	v_mfma_f32_16x16x32_bf16 v[60:63], v[214:217], v[244:247], v[60:63]
	v_mfma_f32_16x16x32_bf16 v[64:67], v[216:219], v[244:247], v[64:67]
	ds_read_b64 v[154:155], v250
	ds_read_b64 v[156:157], v250 offset:32
	ds_read_b64 v[170:171], v250 offset:17408
	ds_read_b64 v[172:173], v250 offset:17440
	ds_read_b64 v[158:159], v250 offset:64
	ds_read_b64 v[160:161], v250 offset:96
	ds_read_b64 v[174:175], v250 offset:17472
	ds_read_b64 v[176:177], v250 offset:17504
	v_pk_mul_f32 v[84:85], v[84:85], v[228:229]
	v_pk_mul_f32 v[86:87], v[86:87], v[230:231]
	v_cvt_pk_bf16_f32 v88, v84, v85
	v_cvt_pk_bf16_f32 v90, v86, v87
	v_lshrrev_b32_e32 v89, 16, v88
	v_lshrrev_b32_e32 v91, 16, v90
	ds_write_b16 v253, v88
	ds_write_b16 v253, v89 offset:272
	ds_write_b16 v253, v90 offset:544
	ds_write_b16 v253, v91 offset:816
	v_cvt_pk_bf16_f32 v186, v36, v37
	v_cvt_pk_bf16_f32 v187, v38, v39
	v_cvt_pk_bf16_f32 v188, v40, v41
	v_cvt_pk_bf16_f32 v189, v42, v43
	s_waitcnt lgkmcnt(8)
	ds_read_b64 v[162:163], v250 offset:128
	ds_read_b64 v[164:165], v250 offset:160
	ds_read_b64 v[178:179], v250 offset:17536
	ds_read_b64 v[180:181], v250 offset:17568
	s_waitcnt lgkmcnt(8)
	v_mfma_f32_16x16x32_bf16 v[80:83], v[154:157], v[186:189], v[80:83]
	v_mfma_f32_16x16x32_bf16 v[84:87], v[170:173], v[186:189], 0
	v_cvt_pk_bf16_f32 v190, v44, v45
	v_cvt_pk_bf16_f32 v191, v46, v47
	v_cvt_pk_bf16_f32 v192, v48, v49
	v_cvt_pk_bf16_f32 v193, v50, v51
	ds_read_b64 v[166:167], v250 offset:192
	ds_read_b64 v[168:169], v250 offset:224
	ds_read_b64 v[182:183], v250 offset:17600
	ds_read_b64 v[184:185], v250 offset:17632
	s_waitcnt lgkmcnt(8)
	v_mfma_f32_16x16x32_bf16 v[80:83], v[158:161], v[190:193], v[80:83]
	v_mfma_f32_16x16x32_bf16 v[84:87], v[174:177], v[190:193], v[84:87]
	v_cvt_pk_bf16_f32 v194, v52, v53
	v_cvt_pk_bf16_f32 v195, v54, v55
	v_cvt_pk_bf16_f32 v196, v56, v57
	v_cvt_pk_bf16_f32 v197, v58, v59
	ds_read_b64 v[202:203], v103 offset:34848
	ds_read_b64 v[204:205], v104 offset:34848
	ds_read_b64 v[206:207], v104 offset:37408
	ds_read_b64 v[208:209], v104 offset:39968
	s_waitcnt lgkmcnt(8)
	v_mfma_f32_16x16x32_bf16 v[80:83], v[162:165], v[194:197], v[80:83]
	v_mfma_f32_16x16x32_bf16 v[84:87], v[178:181], v[194:197], v[84:87]
	v_cvt_pk_bf16_f32 v198, v60, v61
	v_cvt_pk_bf16_f32 v199, v62, v63
	v_cvt_pk_bf16_f32 v200, v64, v65
	v_cvt_pk_bf16_f32 v201, v66, v67
	ds_read_b64 v[210:211], v103 offset:45088
	ds_read_b64 v[212:213], v103 offset:47648
	ds_read_b64 v[214:215], v103 offset:50208
	ds_read_b64 v[216:217], v103 offset:52768
	s_waitcnt lgkmcnt(8)
	v_mfma_f32_16x16x32_bf16 v[80:83], v[166:169], v[198:201], v[80:83]
	v_mfma_f32_16x16x32_bf16 v[84:87], v[182:185], v[198:201], v[84:87]
	ds_read_b128 v[220:223], v106 offset:64
	ds_read_b128 v[224:227], v107 offset:576
	ds_read_b128 v[228:231], v102 offset:64
	ds_read_b64 v[232:233], v252 offset:1280
	v_pk_mul_f32 v[36:37], v[36:37], v[236:237] op_sel:[0,1]
	v_pk_mul_f32 v[38:39], v[38:39], v[236:237] op_sel:[0,1]
	v_pk_mul_f32 v[40:41], v[40:41], v[236:237] op_sel:[0,1]
	v_pk_mul_f32 v[42:43], v[42:43], v[236:237] op_sel:[0,1]
	v_pk_mul_f32 v[44:45], v[44:45], v[236:237] op_sel:[0,1]
	v_pk_mul_f32 v[46:47], v[46:47], v[236:237] op_sel:[0,1]
	v_pk_mul_f32 v[48:49], v[48:49], v[236:237] op_sel:[0,1]
	v_pk_mul_f32 v[50:51], v[50:51], v[236:237] op_sel:[0,1]
	v_pk_mul_f32 v[52:53], v[52:53], v[236:237] op_sel:[0,1]
	v_pk_mul_f32 v[54:55], v[54:55], v[236:237] op_sel:[0,1]
	v_pk_mul_f32 v[56:57], v[56:57], v[236:237] op_sel:[0,1]
	v_pk_mul_f32 v[58:59], v[58:59], v[236:237] op_sel:[0,1]
	v_pk_mul_f32 v[60:61], v[60:61], v[236:237] op_sel:[0,1]
	v_pk_mul_f32 v[62:63], v[62:63], v[236:237] op_sel:[0,1]
	v_pk_mul_f32 v[64:65], v[64:65], v[236:237] op_sel:[0,1]
	v_pk_mul_f32 v[66:67], v[66:67], v[236:237] op_sel:[0,1]
	s_waitcnt lgkmcnt(2)
	v_cvt_pk_bf16_f32 v240, v80, v81
	v_cvt_pk_bf16_f32 v241, v82, v83
	v_pk_mul_f32 v[88:89], v[80:81], v[220:221]
	v_pk_mul_f32 v[90:91], v[82:83], v[222:223]
	v_cvt_pk_bf16_f32 v244, v88, v89
	v_cvt_pk_bf16_f32 v245, v90, v91
	v_pk_mul_f32 v[84:85], v[84:85], v[224:225]
	v_pk_mul_f32 v[86:87], v[86:87], v[226:227]
	s_waitcnt lgkmcnt(0)
	v_mfma_f32_16x16x32_bf16 v[36:39], v[202:205], v[244:247], v[36:39]
	v_mfma_f32_16x16x32_bf16 v[40:43], v[204:207], v[244:247], v[40:43]
	v_mfma_f32_16x16x32_bf16 v[84:87], v[232:235], v[240:243], v[84:87]
	v_add_u32_e32 v250, 8704, v0
	v_mfma_f32_16x16x32_bf16 v[44:47], v[206:209], v[244:247], v[44:47]
	v_mfma_f32_16x16x32_bf16 v[48:51], v[208:211], v[244:247], v[48:51]
	v_mfma_f32_16x16x32_bf16 v[52:55], v[210:213], v[244:247], v[52:55]
	v_mfma_f32_16x16x32_bf16 v[56:59], v[212:215], v[244:247], v[56:59]
	v_mfma_f32_16x16x32_bf16 v[60:63], v[214:217], v[244:247], v[60:63]
	v_mfma_f32_16x16x32_bf16 v[64:67], v[216:219], v[244:247], v[64:67]
	ds_read_b64 v[154:155], v250
	ds_read_b64 v[156:157], v250 offset:32
	ds_read_b64 v[170:171], v250 offset:17408
	ds_read_b64 v[172:173], v250 offset:17440
	ds_read_b64 v[158:159], v250 offset:64
	ds_read_b64 v[160:161], v250 offset:96
	ds_read_b64 v[174:175], v250 offset:17472
	ds_read_b64 v[176:177], v250 offset:17504
	v_pk_mul_f32 v[84:85], v[84:85], v[228:229]
	v_pk_mul_f32 v[86:87], v[86:87], v[230:231]
	v_cvt_pk_bf16_f32 v88, v84, v85
	v_cvt_pk_bf16_f32 v90, v86, v87
	v_lshrrev_b32_e32 v89, 16, v88
	v_lshrrev_b32_e32 v91, 16, v90
	ds_write_b16 v253, v88 offset:4352
	ds_write_b16 v253, v89 offset:4624
	ds_write_b16 v253, v90 offset:4896
	ds_write_b16 v253, v91 offset:5168
	v_cvt_pk_bf16_f32 v186, v36, v37
	v_cvt_pk_bf16_f32 v187, v38, v39
	v_cvt_pk_bf16_f32 v188, v40, v41
	v_cvt_pk_bf16_f32 v189, v42, v43
	s_waitcnt lgkmcnt(8)
	ds_read_b64 v[162:163], v250 offset:128
	ds_read_b64 v[164:165], v250 offset:160
	ds_read_b64 v[178:179], v250 offset:17536
	ds_read_b64 v[180:181], v250 offset:17568
	s_waitcnt lgkmcnt(8)
	v_mfma_f32_16x16x32_bf16 v[76:79], v[154:157], v[186:189], v[76:79]
	v_mfma_f32_16x16x32_bf16 v[84:87], v[170:173], v[186:189], 0
	v_cvt_pk_bf16_f32 v190, v44, v45
	v_cvt_pk_bf16_f32 v191, v46, v47
	v_cvt_pk_bf16_f32 v192, v48, v49
	v_cvt_pk_bf16_f32 v193, v50, v51
	ds_read_b64 v[166:167], v250 offset:192
	ds_read_b64 v[168:169], v250 offset:224
	ds_read_b64 v[182:183], v250 offset:17600
	ds_read_b64 v[184:185], v250 offset:17632
	s_waitcnt lgkmcnt(8)
	v_mfma_f32_16x16x32_bf16 v[76:79], v[158:161], v[190:193], v[76:79]
	v_mfma_f32_16x16x32_bf16 v[84:87], v[174:177], v[190:193], v[84:87]
	v_cvt_pk_bf16_f32 v194, v52, v53
	v_cvt_pk_bf16_f32 v195, v54, v55
	v_cvt_pk_bf16_f32 v196, v56, v57
	v_cvt_pk_bf16_f32 v197, v58, v59
	ds_read_b64 v[202:203], v103 offset:34880
	ds_read_b64 v[204:205], v104 offset:34880
	ds_read_b64 v[206:207], v104 offset:37440
	ds_read_b64 v[208:209], v104 offset:40000
	s_waitcnt lgkmcnt(8)
	v_mfma_f32_16x16x32_bf16 v[76:79], v[162:165], v[194:197], v[76:79]
	v_mfma_f32_16x16x32_bf16 v[84:87], v[178:181], v[194:197], v[84:87]
	v_cvt_pk_bf16_f32 v198, v60, v61
	v_cvt_pk_bf16_f32 v199, v62, v63
	v_cvt_pk_bf16_f32 v200, v64, v65
	v_cvt_pk_bf16_f32 v201, v66, v67
	ds_read_b64 v[210:211], v103 offset:45120
	ds_read_b64 v[212:213], v103 offset:47680
	ds_read_b64 v[214:215], v103 offset:50240
	ds_read_b64 v[216:217], v103 offset:52800
	s_waitcnt lgkmcnt(8)
	v_mfma_f32_16x16x32_bf16 v[76:79], v[166:169], v[198:201], v[76:79]
	v_mfma_f32_16x16x32_bf16 v[84:87], v[182:185], v[198:201], v[84:87]
	ds_read_b128 v[220:223], v106 offset:128
	ds_read_b128 v[224:227], v107 offset:640
	ds_read_b128 v[228:231], v102 offset:128
	ds_read_b64 v[232:233], v252 offset:2560
	v_pk_mul_f32 v[36:37], v[36:37], v[238:239] op_sel_hi:[1,0]
	v_pk_mul_f32 v[38:39], v[38:39], v[238:239] op_sel_hi:[1,0]
	v_pk_mul_f32 v[40:41], v[40:41], v[238:239] op_sel_hi:[1,0]
	v_pk_mul_f32 v[42:43], v[42:43], v[238:239] op_sel_hi:[1,0]
	v_pk_mul_f32 v[44:45], v[44:45], v[238:239] op_sel_hi:[1,0]
	v_pk_mul_f32 v[46:47], v[46:47], v[238:239] op_sel_hi:[1,0]
	v_pk_mul_f32 v[48:49], v[48:49], v[238:239] op_sel_hi:[1,0]
	v_pk_mul_f32 v[50:51], v[50:51], v[238:239] op_sel_hi:[1,0]
	v_pk_mul_f32 v[52:53], v[52:53], v[238:239] op_sel_hi:[1,0]
	v_pk_mul_f32 v[54:55], v[54:55], v[238:239] op_sel_hi:[1,0]
	v_pk_mul_f32 v[56:57], v[56:57], v[238:239] op_sel_hi:[1,0]
	v_pk_mul_f32 v[58:59], v[58:59], v[238:239] op_sel_hi:[1,0]
	v_pk_mul_f32 v[60:61], v[60:61], v[238:239] op_sel_hi:[1,0]
	v_pk_mul_f32 v[62:63], v[62:63], v[238:239] op_sel_hi:[1,0]
	v_pk_mul_f32 v[64:65], v[64:65], v[238:239] op_sel_hi:[1,0]
	v_pk_mul_f32 v[66:67], v[66:67], v[238:239] op_sel_hi:[1,0]
	s_waitcnt lgkmcnt(2)
	v_cvt_pk_bf16_f32 v240, v76, v77
	v_cvt_pk_bf16_f32 v241, v78, v79
	v_pk_mul_f32 v[88:89], v[76:77], v[220:221]
	v_pk_mul_f32 v[90:91], v[78:79], v[222:223]
	v_cvt_pk_bf16_f32 v244, v88, v89
	v_cvt_pk_bf16_f32 v245, v90, v91
	v_pk_mul_f32 v[84:85], v[84:85], v[224:225]
	v_pk_mul_f32 v[86:87], v[86:87], v[226:227]
	s_waitcnt lgkmcnt(0)
	v_mfma_f32_16x16x32_bf16 v[36:39], v[202:205], v[244:247], v[36:39]
	v_mfma_f32_16x16x32_bf16 v[40:43], v[204:207], v[244:247], v[40:43]
	v_mfma_f32_16x16x32_bf16 v[84:87], v[232:235], v[240:243], v[84:87]
	v_add_u32_e32 v250, 13056, v0
	v_mfma_f32_16x16x32_bf16 v[44:47], v[206:209], v[244:247], v[44:47]
	v_mfma_f32_16x16x32_bf16 v[48:51], v[208:211], v[244:247], v[48:51]
	v_mfma_f32_16x16x32_bf16 v[52:55], v[210:213], v[244:247], v[52:55]
	v_mfma_f32_16x16x32_bf16 v[56:59], v[212:215], v[244:247], v[56:59]
	v_mfma_f32_16x16x32_bf16 v[60:63], v[214:217], v[244:247], v[60:63]
	v_mfma_f32_16x16x32_bf16 v[64:67], v[216:219], v[244:247], v[64:67]
	ds_read_b64 v[154:155], v250
	ds_read_b64 v[156:157], v250 offset:32
	ds_read_b64 v[170:171], v250 offset:17408
	ds_read_b64 v[172:173], v250 offset:17440
	ds_read_b64 v[158:159], v250 offset:64
	ds_read_b64 v[160:161], v250 offset:96
	ds_read_b64 v[174:175], v250 offset:17472
	ds_read_b64 v[176:177], v250 offset:17504
	v_pk_mul_f32 v[84:85], v[84:85], v[228:229]
	v_pk_mul_f32 v[86:87], v[86:87], v[230:231]
	v_cvt_pk_bf16_f32 v88, v84, v85
	v_cvt_pk_bf16_f32 v90, v86, v87
	v_lshrrev_b32_e32 v89, 16, v88
	v_lshrrev_b32_e32 v91, 16, v90
	ds_write_b16 v253, v88 offset:8704
	ds_write_b16 v253, v89 offset:8976
	ds_write_b16 v253, v90 offset:9248
	ds_write_b16 v253, v91 offset:9520
	v_cvt_pk_bf16_f32 v186, v36, v37
	v_cvt_pk_bf16_f32 v187, v38, v39
	v_cvt_pk_bf16_f32 v188, v40, v41
	v_cvt_pk_bf16_f32 v189, v42, v43
	s_waitcnt lgkmcnt(8)
	ds_read_b64 v[162:163], v250 offset:128
	ds_read_b64 v[164:165], v250 offset:160
	ds_read_b64 v[178:179], v250 offset:17536
	ds_read_b64 v[180:181], v250 offset:17568
	s_waitcnt lgkmcnt(8)
	v_mfma_f32_16x16x32_bf16 v[72:75], v[154:157], v[186:189], v[72:75]
	v_mfma_f32_16x16x32_bf16 v[84:87], v[170:173], v[186:189], 0
	v_cvt_pk_bf16_f32 v190, v44, v45
	v_cvt_pk_bf16_f32 v191, v46, v47
	v_cvt_pk_bf16_f32 v192, v48, v49
	v_cvt_pk_bf16_f32 v193, v50, v51
	ds_read_b64 v[166:167], v250 offset:192
	ds_read_b64 v[168:169], v250 offset:224
	ds_read_b64 v[182:183], v250 offset:17600
	ds_read_b64 v[184:185], v250 offset:17632
	s_waitcnt lgkmcnt(8)
	v_mfma_f32_16x16x32_bf16 v[72:75], v[158:161], v[190:193], v[72:75]
	v_mfma_f32_16x16x32_bf16 v[84:87], v[174:177], v[190:193], v[84:87]
	v_cvt_pk_bf16_f32 v194, v52, v53
	v_cvt_pk_bf16_f32 v195, v54, v55
	v_cvt_pk_bf16_f32 v196, v56, v57
	v_cvt_pk_bf16_f32 v197, v58, v59
	ds_read_b64 v[202:203], v103 offset:34912
	ds_read_b64 v[204:205], v104 offset:34912
	ds_read_b64 v[206:207], v104 offset:37472
	ds_read_b64 v[208:209], v104 offset:40032
	s_waitcnt lgkmcnt(8)
	v_mfma_f32_16x16x32_bf16 v[72:75], v[162:165], v[194:197], v[72:75]
	v_mfma_f32_16x16x32_bf16 v[84:87], v[178:181], v[194:197], v[84:87]
	v_cvt_pk_bf16_f32 v198, v60, v61
	v_cvt_pk_bf16_f32 v199, v62, v63
	v_cvt_pk_bf16_f32 v200, v64, v65
	v_cvt_pk_bf16_f32 v201, v66, v67
	ds_read_b64 v[210:211], v103 offset:45152
	ds_read_b64 v[212:213], v103 offset:47712
	ds_read_b64 v[214:215], v103 offset:50272
	ds_read_b64 v[216:217], v103 offset:52832
	s_waitcnt lgkmcnt(8)
	v_mfma_f32_16x16x32_bf16 v[72:75], v[166:169], v[198:201], v[72:75]
	v_mfma_f32_16x16x32_bf16 v[84:87], v[182:185], v[198:201], v[84:87]
	ds_read_b128 v[220:223], v106 offset:192
	ds_read_b128 v[224:227], v107 offset:704
	ds_read_b128 v[228:231], v102 offset:192
	ds_read_b64 v[232:233], v252 offset:3840
	v_pk_mul_f32 v[36:37], v[36:37], v[238:239] op_sel:[0,1]
	v_pk_mul_f32 v[38:39], v[38:39], v[238:239] op_sel:[0,1]
	v_pk_mul_f32 v[40:41], v[40:41], v[238:239] op_sel:[0,1]
	v_pk_mul_f32 v[42:43], v[42:43], v[238:239] op_sel:[0,1]
	v_pk_mul_f32 v[44:45], v[44:45], v[238:239] op_sel:[0,1]
	v_pk_mul_f32 v[46:47], v[46:47], v[238:239] op_sel:[0,1]
	v_pk_mul_f32 v[48:49], v[48:49], v[238:239] op_sel:[0,1]
	v_pk_mul_f32 v[50:51], v[50:51], v[238:239] op_sel:[0,1]
	v_pk_mul_f32 v[52:53], v[52:53], v[238:239] op_sel:[0,1]
	v_pk_mul_f32 v[54:55], v[54:55], v[238:239] op_sel:[0,1]
	v_pk_mul_f32 v[56:57], v[56:57], v[238:239] op_sel:[0,1]
	v_pk_mul_f32 v[58:59], v[58:59], v[238:239] op_sel:[0,1]
	v_pk_mul_f32 v[60:61], v[60:61], v[238:239] op_sel:[0,1]
	v_pk_mul_f32 v[62:63], v[62:63], v[238:239] op_sel:[0,1]
	v_pk_mul_f32 v[64:65], v[64:65], v[238:239] op_sel:[0,1]
	v_pk_mul_f32 v[66:67], v[66:67], v[238:239] op_sel:[0,1]
	s_waitcnt lgkmcnt(2)
	v_cvt_pk_bf16_f32 v240, v72, v73
	v_cvt_pk_bf16_f32 v241, v74, v75
	v_pk_mul_f32 v[88:89], v[72:73], v[220:221]
	v_pk_mul_f32 v[90:91], v[74:75], v[222:223]
	v_cvt_pk_bf16_f32 v244, v88, v89
	v_cvt_pk_bf16_f32 v245, v90, v91
	v_pk_mul_f32 v[84:85], v[84:85], v[224:225]
	v_pk_mul_f32 v[86:87], v[86:87], v[226:227]
	s_waitcnt lgkmcnt(0)
	v_mfma_f32_16x16x32_bf16 v[36:39], v[202:205], v[244:247], v[36:39]
	v_mfma_f32_16x16x32_bf16 v[40:43], v[204:207], v[244:247], v[40:43]
	v_mfma_f32_16x16x32_bf16 v[84:87], v[232:235], v[240:243], v[84:87]
	v_mfma_f32_16x16x32_bf16 v[44:47], v[206:209], v[244:247], v[44:47]
	v_mfma_f32_16x16x32_bf16 v[48:51], v[208:211], v[244:247], v[48:51]
	v_mfma_f32_16x16x32_bf16 v[52:55], v[210:213], v[244:247], v[52:55]
	v_mfma_f32_16x16x32_bf16 v[56:59], v[212:215], v[244:247], v[56:59]
	v_mfma_f32_16x16x32_bf16 v[60:63], v[214:217], v[244:247], v[60:63]
	v_mfma_f32_16x16x32_bf16 v[64:67], v[216:219], v[244:247], v[64:67]
	s_nop 1
	v_pk_mul_f32 v[84:85], v[84:85], v[228:229]
	v_pk_mul_f32 v[86:87], v[86:87], v[230:231]
	v_cvt_pk_bf16_f32 v88, v84, v85
	v_cvt_pk_bf16_f32 v90, v86, v87
	v_lshrrev_b32_e32 v89, 16, v88
	v_lshrrev_b32_e32 v91, 16, v90
	ds_write_b16 v253, v88 offset:13056
	ds_write_b16 v253, v89 offset:13328
	ds_write_b16 v253, v90 offset:13600
	ds_write_b16 v253, v91 offset:13872
	s_waitcnt lgkmcnt(0)
	s_barrier
	s_waitcnt lgkmcnt(0)
	s_cbranch_scc1 .LBB0_1021
